# P5 pass-1 scan step loop hand-rewritten: 4x4-block state layout, decay folded into a running per-column scale (state renormalised every 64 steps), rank-1/2 updates on f32 v_mfma_4x4x1_16b, dots on VAL
# speedup vs baseline: 1.0289x; 1.0221x over previous
; #define LAS __attribute__((address_space(3)))
;     ...
;     const int tid = threadIdx.x, lane = tid & 63, wave = tid >> 6, G = gridDim.x;
;     const int gw = blockIdx.x * NWAVES + wave, NGW = G * NWAVES;
;     unsigned char* ws = p.ws;
;     const float* DEC = (const float*)(ws + WS_DEC);
;     const bf16* R = (const bf16*)p.out; const bf16* KF = R + (size_t)T * DB; const bf16* V = KF + (size_t)T * DB; const bf16* KKN = V + (size_t)T * DB; const bf16* Bv = (const bf16*)(ws + WS_B);
;     const bf16* Gt = (const bf16*)(ws + WS_G); const float* BON = (const float*)(ws + WS_BONUS); bf16* YB = (bf16*)(ws + WS_YB);
;     float* ST = (float*)(ws + WS_ST); float* YT = (float*)p.out; bf16* ZT = (bf16*)p.out + (size_t)3 * T * DB;
;     const bf16* FEAT = (const bf16*)(ws + WS_FEAT); const bf16* AS = (const bf16*)(ws + WS_AS); bf16* Vw = (bf16*)p.out + (size_t)2 * T * DB; float* BONw = (float*)(ws + WS_BONUS);
;     LAS float* buf = (LAS float*)(lds + wave * 16384);
;     for (int u = gw; u < 32 * NCH; u += NGW) {
;         const int bh = u / NCH, ch = u % NCH, b = bh >> 4, h = bh & 15; int lnl = lane; asm volatile("" : "+v"(lnl));
;         const unsigned i0 = (unsigned)((b * SEQ + ch * CL) * DB + h * 64) + (unsigned)lnl;
;         const unsigned q0 = (unsigned)((b * SEQ + ch * CL) * NH + h);
;         const unsigned f0 = (unsigned)((b * SEQ + ch * CL) * 3072 + h * 64) + (unsigned)lnl;
;         const int cc_ = h * 64 + lnl;
;         const float mur = p.in[I_MU][cc_], muk = p.in[I_MU][1024 + cc_], muv = p.in[I_MU][2048 + cc_], ckk = p.in[I_KK][cc_], cka = p.in[I_KA][cc_], crk = p.in[I_RK][cc_];
;     ...
;         if (!PASS2 && MODE == 0) { f32x4* sq = (f32x4*)(ST + ((size_t)u * 2) * 4096 + lane * 64); f32x4* sp = (f32x4*)(ST + ((size_t)u * 2 + 1) * 4096 + lane * 64);
; #pragma unroll
;             for (int j = 0; j < 16; ++j) { sq[j] = (f32x4){Q2[2 * j].x, Q2[2 * j].y, Q2[2 * j + 1].x, Q2[2 * j + 1].y}; sp[j] = (f32x4){P2[2 * j].x, P2[2 * j].y, P2[2 * j + 1].x, P2[2 * j + 1].y}; } }
.LBB0_1048:
	s_cmp_lt_i32 s30, 6
	s_cselect_b64 s[0:1], -1, 0
	s_cmp_gt_i32 s31, 5
	s_cselect_b64 s[4:5], -1, 0
	s_and_b64 s[4:5], s[0:1], s[4:5]
	s_andn2_b64 vcc, exec, s[4:5]
	s_cbranch_vccnz .LBB0_1080
	v_lshl_add_u32 v128, s96, 3, v145
	s_movk_i32 s3, 0x800
	v_cmp_gt_i32_e32 vcc, s3, v128
	s_and_saveexec_b64 s[6:7], vcc
	s_cbranch_execz .LBB0_1079
	v_readlane_b32 s4, v244, 0
	s_lshl_b32 s3, s4, 3
	s_add_u32 s8, s28, 0x10800000
	s_addc_u32 s9, s29, 0
	s_add_u32 s10, s28, 0x38000000
	s_addc_u32 s11, s29, 0
	s_add_u32 s12, s26, 0xc000000
	s_addc_u32 s13, s27, 0
	s_add_u32 s14, s28, 0x18800000
	s_addc_u32 s15, s29, 0
	s_add_u32 s16, s28, 0x28000000
	s_addc_u32 s17, s29, 0
	s_add_u32 s18, s26, 0x8000000
	v_and_b32_e32 v147, 63, v144
	s_addc_u32 s19, s27, 0
	v_readlane_b32 s5, v244, 1
	s_add_u32 s36, s28, 0x8500000
	v_lshl_add_u32 v151, v145, 14, 0
	v_lshlrev_b32_e32 v155, 2, v147
	s_waitcnt lgkmcnt(0)
	v_and_b32_e32 v1, 15, v144
	v_lshlrev_b32_e32 v0, 6, v147
	s_addc_u32 s37, s29, 0
	v_add_u32_e32 v180, v151, v155
	v_cmp_eq_u32_e64 s[4:5], 0, v147
	v_mov_b32_e32 v131, 0
	v_lshlrev_b32_e32 v181, 2, v1
	s_mov_b64 s[38:39], 0
	s_movk_i32 s33, 0x1000
	s_movk_i32 s40, 0x1800
	s_movk_i32 s41, 0x7fff
	v_lshlrev_b32_e32 v132, 2, v0
	s_mov_b64 s[52:53], 0x4000
	s_movk_i32 s42, 0x7ff
	v_and_b32_e32 v246, 3, v147
	v_and_b32_e32 v245, 60, v147
	v_lshl_or_b32 v245, v246, 6, v245
	v_add_u32_e32 v180, v151, v245
	s_mov_b32 s86, 0x22222222
	s_mov_b32 s87, 0x22222222
	s_mov_b32 s88, 0x44444444
	s_mov_b32 s89, 0x44444444
	s_mov_b32 s84, 0x88888888
	s_mov_b32 s85, 0x88888888
	s_branch .LBB0_1052
.LBB0_1051:
	v_add_u32_e32 v130, v151, v245
	ds_write_b32 v130, v246 offset:12288
	v_and_b32_e32 v255, 0xc0, v245
	v_add_u32_e32 v255, v255, v151
	ds_read_b128 v[192:195], v255 offset:12288
	ds_read_b128 v[196:199], v255 offset:12304
	ds_read_b128 v[200:203], v255 offset:12320
	ds_read_b128 v[204:207], v255 offset:12336
	s_waitcnt lgkmcnt(0)
	v_mul_f32_e32 v0, v0, v192
	v_mul_f32_e32 v64, v64, v192
	v_mul_f32_e32 v1, v1, v192
	v_mul_f32_e32 v65, v65, v192
	v_mul_f32_e32 v2, v2, v192
	v_mul_f32_e32 v66, v66, v192
	v_mul_f32_e32 v3, v3, v192
	v_mul_f32_e32 v67, v67, v192
	v_mul_f32_e32 v4, v4, v193
	v_mul_f32_e32 v68, v68, v193
	v_mul_f32_e32 v5, v5, v193
	v_mul_f32_e32 v69, v69, v193
	v_mul_f32_e32 v6, v6, v193
	v_mul_f32_e32 v70, v70, v193
	v_mul_f32_e32 v7, v7, v193
	v_mul_f32_e32 v71, v71, v193
	v_mul_f32_e32 v8, v8, v194
	v_mul_f32_e32 v72, v72, v194
	v_mul_f32_e32 v9, v9, v194
	v_mul_f32_e32 v73, v73, v194
	v_mul_f32_e32 v10, v10, v194
	v_mul_f32_e32 v74, v74, v194
	v_mul_f32_e32 v11, v11, v194
	v_mul_f32_e32 v75, v75, v194
	v_mul_f32_e32 v12, v12, v195
	v_mul_f32_e32 v76, v76, v195
	v_mul_f32_e32 v13, v13, v195
	v_mul_f32_e32 v77, v77, v195
	v_mul_f32_e32 v14, v14, v195
	v_mul_f32_e32 v78, v78, v195
	v_mul_f32_e32 v15, v15, v195
	v_mul_f32_e32 v79, v79, v195
	v_mul_f32_e32 v16, v16, v196
	v_mul_f32_e32 v80, v80, v196
	v_mul_f32_e32 v17, v17, v196
	v_mul_f32_e32 v81, v81, v196
	v_mul_f32_e32 v18, v18, v196
	v_mul_f32_e32 v82, v82, v196
	v_mul_f32_e32 v19, v19, v196
	v_mul_f32_e32 v83, v83, v196
	v_mul_f32_e32 v20, v20, v197
	v_mul_f32_e32 v84, v84, v197
	v_mul_f32_e32 v21, v21, v197
	v_mul_f32_e32 v85, v85, v197
	v_mul_f32_e32 v22, v22, v197
	v_mul_f32_e32 v86, v86, v197
	v_mul_f32_e32 v23, v23, v197
	v_mul_f32_e32 v87, v87, v197
	v_mul_f32_e32 v24, v24, v198
	v_mul_f32_e32 v88, v88, v198
	v_mul_f32_e32 v25, v25, v198
	v_mul_f32_e32 v89, v89, v198
	v_mul_f32_e32 v26, v26, v198
	v_mul_f32_e32 v90, v90, v198
	v_mul_f32_e32 v27, v27, v198
	v_mul_f32_e32 v91, v91, v198
	v_mul_f32_e32 v28, v28, v199
	v_mul_f32_e32 v92, v92, v199
	v_mul_f32_e32 v29, v29, v199
	v_mul_f32_e32 v93, v93, v199
	v_mul_f32_e32 v30, v30, v199
	v_mul_f32_e32 v94, v94, v199
	v_mul_f32_e32 v31, v31, v199
	v_mul_f32_e32 v95, v95, v199
	v_mul_f32_e32 v32, v32, v200
	v_mul_f32_e32 v96, v96, v200
	v_mul_f32_e32 v33, v33, v200
	v_mul_f32_e32 v97, v97, v200
	v_mul_f32_e32 v34, v34, v200
	v_mul_f32_e32 v98, v98, v200
	v_mul_f32_e32 v35, v35, v200
	v_mul_f32_e32 v99, v99, v200
	v_mul_f32_e32 v36, v36, v201
	v_mul_f32_e32 v100, v100, v201
	v_mul_f32_e32 v37, v37, v201
	v_mul_f32_e32 v101, v101, v201
	v_mul_f32_e32 v38, v38, v201
	v_mul_f32_e32 v102, v102, v201
	v_mul_f32_e32 v39, v39, v201
	v_mul_f32_e32 v103, v103, v201
	v_mul_f32_e32 v40, v40, v202
	v_mul_f32_e32 v104, v104, v202
	v_mul_f32_e32 v41, v41, v202
	v_mul_f32_e32 v105, v105, v202
	v_mul_f32_e32 v42, v42, v202
	v_mul_f32_e32 v106, v106, v202
	v_mul_f32_e32 v43, v43, v202
	v_mul_f32_e32 v107, v107, v202
	v_mul_f32_e32 v44, v44, v203
	v_mul_f32_e32 v108, v108, v203
	v_mul_f32_e32 v45, v45, v203
	v_mul_f32_e32 v109, v109, v203
	v_mul_f32_e32 v46, v46, v203
	v_mul_f32_e32 v110, v110, v203
	v_mul_f32_e32 v47, v47, v203
	v_mul_f32_e32 v111, v111, v203
	v_mul_f32_e32 v48, v48, v204
	v_mul_f32_e32 v112, v112, v204
	v_mul_f32_e32 v49, v49, v204
	v_mul_f32_e32 v113, v113, v204
	v_mul_f32_e32 v50, v50, v204
	v_mul_f32_e32 v114, v114, v204
	v_mul_f32_e32 v51, v51, v204
	v_mul_f32_e32 v115, v115, v204
	v_mul_f32_e32 v52, v52, v205
	v_mul_f32_e32 v116, v116, v205
	v_mul_f32_e32 v53, v53, v205
	v_mul_f32_e32 v117, v117, v205
	v_mul_f32_e32 v54, v54, v205
	v_mul_f32_e32 v118, v118, v205
	v_mul_f32_e32 v55, v55, v205
	v_mul_f32_e32 v119, v119, v205
	v_mul_f32_e32 v56, v56, v206
	v_mul_f32_e32 v120, v120, v206
	v_mul_f32_e32 v57, v57, v206
	v_mul_f32_e32 v121, v121, v206
	v_mul_f32_e32 v58, v58, v206
	v_mul_f32_e32 v122, v122, v206
	v_mul_f32_e32 v59, v59, v206
	v_mul_f32_e32 v123, v123, v206
	v_mul_f32_e32 v60, v60, v207
	v_mul_f32_e32 v124, v124, v207
;     ...
;         if (!PASS2 && MODE == 0) { f32x4* sq = (f32x4*)(ST + ((size_t)u * 2) * 4096 + lane * 64); f32x4* sp = (f32x4*)(ST + ((size_t)u * 2 + 1) * 4096 + lane * 64);
; #pragma unroll
;             for (int j = 0; j < 16; ++j) { sq[j] = (f32x4){Q2[2 * j].x, Q2[2 * j].y, Q2[2 * j + 1].x, Q2[2 * j + 1].y}; sp[j] = (f32x4){P2[2 * j].x, P2[2 * j].y, P2[2 * j + 1].x, P2[2 * j + 1].y}; } }
	v_mul_f32_e32 v61, v61, v207
	v_mul_f32_e32 v125, v125, v207
	v_mul_f32_e32 v62, v62, v207
	v_mul_f32_e32 v126, v126, v207
	v_mul_f32_e32 v63, v63, v207
	v_mul_f32_e32 v127, v127, v207
	v_mov_b32_e32 v246, 1.0
	v_lshlrev_b64 v[134:135], 15, v[128:129]
	v_lshl_add_u64 v[134:135], s[10:11], 0, v[134:135]
	v_and_b32_e32 v130, 60, v147
	v_lshlrev_b32_e32 v130, 8, v130
	v_and_b32_e32 v136, 3, v147
	v_lshl_or_b32 v130, v136, 2, v130
	v_lshl_add_u64 v[134:135], v[134:135], 0, v[130:131]
	v_lshl_add_u64 v[136:137], v[134:135], 0, s[52:53]
	global_store_dword v[134:135], v0, off offset:0
	global_store_dword v[134:135], v1, off offset:256
	global_store_dword v[134:135], v2, off offset:512
	global_store_dword v[134:135], v3, off offset:768
	global_store_dword v[134:135], v4, off offset:16
	global_store_dword v[134:135], v5, off offset:272
	global_store_dword v[134:135], v6, off offset:528
	global_store_dword v[134:135], v7, off offset:784
	global_store_dword v[134:135], v8, off offset:32
	global_store_dword v[134:135], v9, off offset:288
	global_store_dword v[134:135], v10, off offset:544
	global_store_dword v[134:135], v11, off offset:800
	global_store_dword v[134:135], v12, off offset:48
	global_store_dword v[134:135], v13, off offset:304
	global_store_dword v[134:135], v14, off offset:560
	global_store_dword v[134:135], v15, off offset:816
	global_store_dword v[134:135], v16, off offset:64
	global_store_dword v[134:135], v17, off offset:320
	global_store_dword v[134:135], v18, off offset:576
	global_store_dword v[134:135], v19, off offset:832
	global_store_dword v[134:135], v20, off offset:80
	global_store_dword v[134:135], v21, off offset:336
	global_store_dword v[134:135], v22, off offset:592
	global_store_dword v[134:135], v23, off offset:848
	global_store_dword v[134:135], v24, off offset:96
	global_store_dword v[134:135], v25, off offset:352
	global_store_dword v[134:135], v26, off offset:608
	global_store_dword v[134:135], v27, off offset:864
	global_store_dword v[134:135], v28, off offset:112
	global_store_dword v[134:135], v29, off offset:368
	global_store_dword v[134:135], v30, off offset:624
	global_store_dword v[134:135], v31, off offset:880
	global_store_dword v[134:135], v32, off offset:128
	global_store_dword v[134:135], v33, off offset:384
	global_store_dword v[134:135], v34, off offset:640
	global_store_dword v[134:135], v35, off offset:896
	global_store_dword v[134:135], v36, off offset:144
	global_store_dword v[134:135], v37, off offset:400
	global_store_dword v[134:135], v38, off offset:656
	global_store_dword v[134:135], v39, off offset:912
	global_store_dword v[134:135], v40, off offset:160
	global_store_dword v[134:135], v41, off offset:416
	global_store_dword v[134:135], v42, off offset:672
	global_store_dword v[134:135], v43, off offset:928
	global_store_dword v[134:135], v44, off offset:176
	global_store_dword v[134:135], v45, off offset:432
	global_store_dword v[134:135], v46, off offset:688
	global_store_dword v[134:135], v47, off offset:944
	global_store_dword v[134:135], v48, off offset:192
	global_store_dword v[134:135], v49, off offset:448
	global_store_dword v[134:135], v50, off offset:704
	global_store_dword v[134:135], v51, off offset:960
	global_store_dword v[134:135], v52, off offset:208
	global_store_dword v[134:135], v53, off offset:464
	global_store_dword v[134:135], v54, off offset:720
	global_store_dword v[134:135], v55, off offset:976
	global_store_dword v[134:135], v56, off offset:224
	global_store_dword v[134:135], v57, off offset:480
	global_store_dword v[134:135], v58, off offset:736
	global_store_dword v[134:135], v59, off offset:992
	global_store_dword v[134:135], v60, off offset:240
;     ...
;     for (int u = gw; u < 32 * NCH; u += NGW) {
;     ...
;         if (!PASS2 && MODE == 0) { f32x4* sq = (f32x4*)(ST + ((size_t)u * 2) * 4096 + lane * 64); f32x4* sp = (f32x4*)(ST + ((size_t)u * 2 + 1) * 4096 + lane * 64);
; #pragma unroll
;             for (int j = 0; j < 16; ++j) { sq[j] = (f32x4){Q2[2 * j].x, Q2[2 * j].y, Q2[2 * j + 1].x, Q2[2 * j + 1].y}; sp[j] = (f32x4){P2[2 * j].x, P2[2 * j].y, P2[2 * j + 1].x, P2[2 * j + 1].y}; } }
	global_store_dword v[134:135], v61, off offset:496
	global_store_dword v[134:135], v62, off offset:752
	global_store_dword v[134:135], v63, off offset:1008
	global_store_dword v[136:137], v64, off offset:0
	global_store_dword v[136:137], v65, off offset:256
	global_store_dword v[136:137], v66, off offset:512
	global_store_dword v[136:137], v67, off offset:768
	global_store_dword v[136:137], v68, off offset:16
	global_store_dword v[136:137], v69, off offset:272
	global_store_dword v[136:137], v70, off offset:528
	global_store_dword v[136:137], v71, off offset:784
	global_store_dword v[136:137], v72, off offset:32
	global_store_dword v[136:137], v73, off offset:288
	global_store_dword v[136:137], v74, off offset:544
	global_store_dword v[136:137], v75, off offset:800
	global_store_dword v[136:137], v76, off offset:48
	global_store_dword v[136:137], v77, off offset:304
	global_store_dword v[136:137], v78, off offset:560
	global_store_dword v[136:137], v79, off offset:816
	global_store_dword v[136:137], v80, off offset:64
	global_store_dword v[136:137], v81, off offset:320
	global_store_dword v[136:137], v82, off offset:576
	global_store_dword v[136:137], v83, off offset:832
	global_store_dword v[136:137], v84, off offset:80
	global_store_dword v[136:137], v85, off offset:336
	global_store_dword v[136:137], v86, off offset:592
	global_store_dword v[136:137], v87, off offset:848
	global_store_dword v[136:137], v88, off offset:96
	global_store_dword v[136:137], v89, off offset:352
	global_store_dword v[136:137], v90, off offset:608
	global_store_dword v[136:137], v91, off offset:864
	global_store_dword v[136:137], v92, off offset:112
	global_store_dword v[136:137], v93, off offset:368
	global_store_dword v[136:137], v94, off offset:624
	global_store_dword v[136:137], v95, off offset:880
	global_store_dword v[136:137], v96, off offset:128
	global_store_dword v[136:137], v97, off offset:384
	global_store_dword v[136:137], v98, off offset:640
	global_store_dword v[136:137], v99, off offset:896
	global_store_dword v[136:137], v100, off offset:144
	global_store_dword v[136:137], v101, off offset:400
	global_store_dword v[136:137], v102, off offset:656
	global_store_dword v[136:137], v103, off offset:912
	global_store_dword v[136:137], v104, off offset:160
	global_store_dword v[136:137], v105, off offset:416
	global_store_dword v[136:137], v106, off offset:672
	global_store_dword v[136:137], v107, off offset:928
	global_store_dword v[136:137], v108, off offset:176
	global_store_dword v[136:137], v109, off offset:432
	global_store_dword v[136:137], v110, off offset:688
	global_store_dword v[136:137], v111, off offset:944
	global_store_dword v[136:137], v112, off offset:192
	global_store_dword v[136:137], v113, off offset:448
	global_store_dword v[136:137], v114, off offset:704
	global_store_dword v[136:137], v115, off offset:960
	global_store_dword v[136:137], v116, off offset:208
	global_store_dword v[136:137], v117, off offset:464
	global_store_dword v[136:137], v118, off offset:720
	global_store_dword v[136:137], v119, off offset:976
	global_store_dword v[136:137], v120, off offset:224
	global_store_dword v[136:137], v121, off offset:480
	global_store_dword v[136:137], v122, off offset:736
	global_store_dword v[136:137], v123, off offset:992
	global_store_dword v[136:137], v124, off offset:240
	global_store_dword v[136:137], v125, off offset:496
	global_store_dword v[136:137], v126, off offset:752
	global_store_dword v[136:137], v127, off offset:1008
	v_add_u32_e32 v128, s3, v128
	v_cmp_lt_i32_e32 vcc, s42, v128
	s_or_b64 s[38:39], vcc, s[38:39]
	s_andn2_b64 exec, exec, s[38:39]
	s_cbranch_execz .LBB0_1079

;     ...
;         f32x2 Q2[32], P2[32];
; #pragma unroll
;         for (int k = 0; k < 32; ++k) { Q2[k] = (f32x2){0.f, 0.f}; P2[k] = (f32x2){(2 * k == lnl) ? 1.f : 0.f, (2 * k + 1 == lnl) ? 1.f : 0.f}; }
.LBB0_1062:
	s_or_b64 exec, exec, s[64:65]
	v_cmp_eq_u32_e32 vcc, 0, v65
	v_lshlrev_b32_e32 v67, 20, v64
	v_and_b32_e32 v67, 0xff000000, v67
	v_cndmask_b32_e64 v0, 0, 1.0, vcc
	v_cmp_eq_u32_e32 vcc, 1, v65
	v_lshlrev_b32_e32 v64, 24, v64
	v_mov_b32_e32 v130, v131
	v_cndmask_b32_e64 v1, 0, 1.0, vcc
	v_cmp_eq_u32_e32 vcc, 2, v65
	s_mov_b32 s43, 0
	s_mov_b64 s[64:65], 0
	v_cndmask_b32_e64 v2, 0, 1.0, vcc
	v_cmp_eq_u32_e32 vcc, 3, v65
	v_mov_b64_e32 v[70:71], v[130:131]
	v_mov_b64_e32 v[68:69], v[130:131]
	v_cndmask_b32_e64 v3, 0, 1.0, vcc
	v_cmp_eq_u32_e32 vcc, 4, v65
	v_mov_b64_e32 v[74:75], v[130:131]
	v_mov_b64_e32 v[72:73], v[130:131]
	v_cndmask_b32_e64 v4, 0, 1.0, vcc
	v_cmp_eq_u32_e32 vcc, 5, v65
	v_mov_b64_e32 v[78:79], v[130:131]
	v_mov_b64_e32 v[76:77], v[130:131]
	v_cndmask_b32_e64 v5, 0, 1.0, vcc
	v_cmp_eq_u32_e32 vcc, 6, v65
	v_mov_b64_e32 v[86:87], v[130:131]
	v_mov_b64_e32 v[84:85], v[130:131]
	v_cndmask_b32_e64 v6, 0, 1.0, vcc
	v_cmp_eq_u32_e32 vcc, 7, v65
	v_mov_b64_e32 v[94:95], v[130:131]
	v_mov_b64_e32 v[92:93], v[130:131]
	v_cndmask_b32_e64 v7, 0, 1.0, vcc
	v_cmp_eq_u32_e32 vcc, 8, v65
	v_mov_b64_e32 v[98:99], v[130:131]
	v_mov_b64_e32 v[96:97], v[130:131]
	v_cndmask_b32_e64 v8, 0, 1.0, vcc
	v_cmp_eq_u32_e32 vcc, 9, v65
	v_mov_b64_e32 v[102:103], v[130:131]
	v_mov_b64_e32 v[100:101], v[130:131]
	v_cndmask_b32_e64 v9, 0, 1.0, vcc
	v_cmp_eq_u32_e32 vcc, 10, v65
	v_mov_b64_e32 v[106:107], v[130:131]
	v_mov_b64_e32 v[104:105], v[130:131]
	v_cndmask_b32_e64 v10, 0, 1.0, vcc
	v_cmp_eq_u32_e32 vcc, 11, v65
	v_mov_b64_e32 v[110:111], v[130:131]
	v_mov_b64_e32 v[108:109], v[130:131]
	v_cndmask_b32_e64 v11, 0, 1.0, vcc
	v_cmp_eq_u32_e32 vcc, 12, v65
	v_mov_b64_e32 v[114:115], v[130:131]
	v_mov_b64_e32 v[112:113], v[130:131]
	v_cndmask_b32_e64 v12, 0, 1.0, vcc
	v_cmp_eq_u32_e32 vcc, 13, v65
	v_mov_b64_e32 v[118:119], v[130:131]
	v_mov_b64_e32 v[116:117], v[130:131]
	v_cndmask_b32_e64 v13, 0, 1.0, vcc
	v_cmp_eq_u32_e32 vcc, 14, v65
	v_mov_b64_e32 v[122:123], v[130:131]
	v_mov_b64_e32 v[120:121], v[130:131]
	v_cndmask_b32_e64 v14, 0, 1.0, vcc
	v_cmp_eq_u32_e32 vcc, 15, v65
	v_mov_b64_e32 v[126:127], v[130:131]
	v_mov_b64_e32 v[124:125], v[130:131]
	v_cndmask_b32_e64 v15, 0, 1.0, vcc
	v_cmp_eq_u32_e32 vcc, 16, v65
	v_mov_b64_e32 v[88:89], v[130:131]
	v_mov_b64_e32 v[90:91], v[130:131]
	v_cndmask_b32_e64 v16, 0, 1.0, vcc
	v_cmp_eq_u32_e32 vcc, 17, v65
	v_mov_b64_e32 v[80:81], v[130:131]
	v_mov_b64_e32 v[82:83], v[130:131]
	v_cndmask_b32_e64 v17, 0, 1.0, vcc
	v_cmp_eq_u32_e32 vcc, 18, v65
	v_mov_b64_e32 v[160:161], v[156:157]
	v_mov_b64_e32 v[162:163], v[158:159]
	v_cndmask_b32_e64 v18, 0, 1.0, vcc
	v_cmp_eq_u32_e32 vcc, 19, v65
	s_nop 1
	v_cndmask_b32_e64 v19, 0, 1.0, vcc
	v_cmp_eq_u32_e32 vcc, 20, v65
	s_nop 1
	v_cndmask_b32_e64 v20, 0, 1.0, vcc
	v_cmp_eq_u32_e32 vcc, 21, v65
	s_nop 1
	v_cndmask_b32_e64 v21, 0, 1.0, vcc
	v_cmp_eq_u32_e32 vcc, 22, v65
	s_nop 1
	v_cndmask_b32_e64 v22, 0, 1.0, vcc
	v_cmp_eq_u32_e32 vcc, 23, v65
	s_nop 1
	v_cndmask_b32_e64 v23, 0, 1.0, vcc
	v_cmp_eq_u32_e32 vcc, 24, v65
	s_nop 1
	v_cndmask_b32_e64 v24, 0, 1.0, vcc
	v_cmp_eq_u32_e32 vcc, 25, v65
	s_nop 1
	v_cndmask_b32_e64 v25, 0, 1.0, vcc
	v_cmp_eq_u32_e32 vcc, 26, v65
	s_nop 1
	v_cndmask_b32_e64 v26, 0, 1.0, vcc
	v_cmp_eq_u32_e32 vcc, 27, v65
	s_nop 1
	v_cndmask_b32_e64 v27, 0, 1.0, vcc
	v_cmp_eq_u32_e32 vcc, 28, v65
	s_nop 1
	v_cndmask_b32_e64 v28, 0, 1.0, vcc
	v_cmp_eq_u32_e32 vcc, 29, v65
	s_nop 1
	v_cndmask_b32_e64 v29, 0, 1.0, vcc
	v_cmp_eq_u32_e32 vcc, 30, v65
	s_nop 1
	v_cndmask_b32_e64 v30, 0, 1.0, vcc
	v_cmp_eq_u32_e32 vcc, 31, v65
	s_nop 1
	v_cndmask_b32_e64 v31, 0, 1.0, vcc
	v_cmp_eq_u32_e32 vcc, 32, v65
	s_nop 1
	v_cndmask_b32_e64 v32, 0, 1.0, vcc
	v_cmp_eq_u32_e32 vcc, 33, v65
	s_nop 1
	v_cndmask_b32_e64 v33, 0, 1.0, vcc
	v_cmp_eq_u32_e32 vcc, 34, v65
	s_nop 1
	v_cndmask_b32_e64 v34, 0, 1.0, vcc
	v_cmp_eq_u32_e32 vcc, 35, v65
	s_nop 1
	v_cndmask_b32_e64 v35, 0, 1.0, vcc
	v_cmp_eq_u32_e32 vcc, 36, v65
	s_nop 1
	v_cndmask_b32_e64 v36, 0, 1.0, vcc
	v_cmp_eq_u32_e32 vcc, 37, v65
	s_nop 1
	v_cndmask_b32_e64 v37, 0, 1.0, vcc
	v_cmp_eq_u32_e32 vcc, 38, v65
	s_nop 1
	v_cndmask_b32_e64 v38, 0, 1.0, vcc
	v_cmp_eq_u32_e32 vcc, 39, v65
	s_nop 1
	v_cndmask_b32_e64 v39, 0, 1.0, vcc
	v_cmp_eq_u32_e32 vcc, 40, v65
	s_nop 1
	v_cndmask_b32_e64 v40, 0, 1.0, vcc
	v_cmp_eq_u32_e32 vcc, 41, v65
	s_nop 1
	v_cndmask_b32_e64 v41, 0, 1.0, vcc
	v_cmp_eq_u32_e32 vcc, 42, v65
	s_nop 1
	v_cndmask_b32_e64 v42, 0, 1.0, vcc
	v_cmp_eq_u32_e32 vcc, 43, v65
	s_nop 1
	v_cndmask_b32_e64 v43, 0, 1.0, vcc
	v_cmp_eq_u32_e32 vcc, 44, v65
	s_nop 1
	v_cndmask_b32_e64 v44, 0, 1.0, vcc
	v_cmp_eq_u32_e32 vcc, 45, v65
	s_nop 1
	v_cndmask_b32_e64 v45, 0, 1.0, vcc
	v_cmp_eq_u32_e32 vcc, 46, v65
	s_nop 1
	v_cndmask_b32_e64 v46, 0, 1.0, vcc
	v_cmp_eq_u32_e32 vcc, 47, v65
	s_nop 1
	v_cndmask_b32_e64 v47, 0, 1.0, vcc
	v_cmp_eq_u32_e32 vcc, 48, v65
	s_nop 1
	v_cndmask_b32_e64 v48, 0, 1.0, vcc
	v_cmp_eq_u32_e32 vcc, 49, v65
	s_nop 1
	v_cndmask_b32_e64 v49, 0, 1.0, vcc
	v_cmp_eq_u32_e32 vcc, 50, v65
	s_nop 1
	v_cndmask_b32_e64 v50, 0, 1.0, vcc
	v_cmp_eq_u32_e32 vcc, 51, v65
	s_nop 1
	v_cndmask_b32_e64 v51, 0, 1.0, vcc
	v_cmp_eq_u32_e32 vcc, 52, v65
	s_nop 1
	v_cndmask_b32_e64 v52, 0, 1.0, vcc
	v_cmp_eq_u32_e32 vcc, 53, v65
	s_nop 1
	v_cndmask_b32_e64 v53, 0, 1.0, vcc
	v_cmp_eq_u32_e32 vcc, 54, v65
	s_nop 1
	v_cndmask_b32_e64 v54, 0, 1.0, vcc
	v_cmp_eq_u32_e32 vcc, 55, v65
	s_nop 1
	v_cndmask_b32_e64 v55, 0, 1.0, vcc
	v_cmp_eq_u32_e32 vcc, 56, v65
	s_nop 1
	v_cndmask_b32_e64 v60, 0, 1.0, vcc
	v_cmp_eq_u32_e32 vcc, 57, v65
	s_nop 1
	v_cndmask_b32_e64 v61, 0, 1.0, vcc
	v_cmp_eq_u32_e32 vcc, 58, v65
;     ...
;         f32x2 Q2[32], P2[32];
; #pragma unroll
;         for (int k = 0; k < 32; ++k) { Q2[k] = (f32x2){0.f, 0.f}; P2[k] = (f32x2){(2 * k == lnl) ? 1.f : 0.f, (2 * k + 1 == lnl) ? 1.f : 0.f}; }
	s_nop 1
	v_cndmask_b32_e64 v62, 0, 1.0, vcc
	v_cmp_eq_u32_e32 vcc, 59, v65
	s_nop 1
	v_cndmask_b32_e64 v63, 0, 1.0, vcc
	v_cmp_eq_u32_e32 vcc, 60, v65
	s_nop 1
	v_cndmask_b32_e64 v56, 0, 1.0, vcc
	v_cmp_eq_u32_e32 vcc, 61, v65
	s_nop 1
	v_cndmask_b32_e64 v57, 0, 1.0, vcc
	v_cmp_eq_u32_e32 vcc, 62, v65
	s_nop 1
	v_cndmask_b32_e64 v58, 0, 1.0, vcc
	v_cmp_eq_u32_e32 vcc, 63, v65
	v_add_u32_e32 v65, v65, v67
	v_lshlrev_b32_e32 v67, 18, v128
	v_add3_u32 v65, v65, v67, v66
	v_cndmask_b32_e64 v59, 0, 1.0, vcc
	v_sub_u32_e32 v141, v65, v64
	v_mov_b64_e32 v[66:67], v[130:131]
	v_mov_b64_e32 v[64:65], v[130:131]
	v_mov_b32_e32 v246, 1.0
	v_mov_b32_e32 v0, 0
	v_mov_b32_e32 v1, 0
	v_mov_b32_e32 v2, 0
	v_mov_b32_e32 v3, 0
	v_mov_b32_e32 v4, 0
	v_mov_b32_e32 v5, 0
	v_mov_b32_e32 v6, 0
	v_mov_b32_e32 v7, 0
	v_mov_b32_e32 v8, 0
	v_mov_b32_e32 v9, 0
	v_mov_b32_e32 v10, 0
	v_mov_b32_e32 v11, 0
	v_mov_b32_e32 v12, 0
	v_mov_b32_e32 v13, 0
	v_mov_b32_e32 v14, 0
	v_mov_b32_e32 v15, 0
	v_mov_b32_e32 v16, 0
	v_mov_b32_e32 v17, 0
	v_mov_b32_e32 v18, 0
	v_mov_b32_e32 v19, 0
	v_mov_b32_e32 v20, 0
	v_mov_b32_e32 v21, 0
	v_mov_b32_e32 v22, 0
	v_mov_b32_e32 v23, 0
	v_mov_b32_e32 v24, 0
	v_mov_b32_e32 v25, 0
	v_mov_b32_e32 v26, 0
	v_mov_b32_e32 v27, 0
	v_mov_b32_e32 v28, 0
	v_mov_b32_e32 v29, 0
	v_mov_b32_e32 v30, 0
	v_mov_b32_e32 v31, 0
	v_mov_b32_e32 v32, 0
	v_mov_b32_e32 v33, 0
	v_mov_b32_e32 v34, 0
	v_mov_b32_e32 v35, 0
	v_mov_b32_e32 v36, 0
	v_mov_b32_e32 v37, 0
	v_mov_b32_e32 v38, 0
	v_mov_b32_e32 v39, 0
	v_mov_b32_e32 v40, 0
	v_mov_b32_e32 v41, 0
	v_mov_b32_e32 v42, 0
	v_mov_b32_e32 v43, 0
	v_mov_b32_e32 v44, 0
	v_mov_b32_e32 v45, 0
	v_mov_b32_e32 v46, 0
	v_mov_b32_e32 v47, 0
	v_mov_b32_e32 v48, 0
	v_mov_b32_e32 v49, 0
	v_mov_b32_e32 v50, 0
	v_mov_b32_e32 v51, 0
	v_mov_b32_e32 v52, 0
	v_mov_b32_e32 v53, 0
	v_mov_b32_e32 v54, 0
	v_mov_b32_e32 v55, 0
	v_mov_b32_e32 v56, 0
	v_mov_b32_e32 v57, 0
	v_mov_b32_e32 v58, 0
	v_mov_b32_e32 v59, 0
	v_mov_b32_e32 v60, 0
	v_mov_b32_e32 v61, 0
	v_mov_b32_e32 v62, 0
	v_mov_b32_e32 v63, 0
	v_cmp_eq_u32_e32 vcc, 0, v147
	s_nop 1
	v_cndmask_b32_e64 v64, 0, 1.0, vcc
	v_cmp_eq_u32_e32 vcc, 1, v147
	s_nop 1
	v_cndmask_b32_e64 v65, 0, 1.0, vcc
	v_cmp_eq_u32_e32 vcc, 2, v147
	s_nop 1
	v_cndmask_b32_e64 v66, 0, 1.0, vcc
	v_cmp_eq_u32_e32 vcc, 3, v147
	s_nop 1
	v_cndmask_b32_e64 v67, 0, 1.0, vcc
	v_cmp_eq_u32_e32 vcc, 4, v147
	s_nop 1
	v_cndmask_b32_e64 v68, 0, 1.0, vcc
	v_cmp_eq_u32_e32 vcc, 5, v147
	s_nop 1
	v_cndmask_b32_e64 v69, 0, 1.0, vcc
	v_cmp_eq_u32_e32 vcc, 6, v147
	s_nop 1
	v_cndmask_b32_e64 v70, 0, 1.0, vcc
	v_cmp_eq_u32_e32 vcc, 7, v147
	s_nop 1
	v_cndmask_b32_e64 v71, 0, 1.0, vcc
	v_cmp_eq_u32_e32 vcc, 8, v147
	s_nop 1
	v_cndmask_b32_e64 v72, 0, 1.0, vcc
	v_cmp_eq_u32_e32 vcc, 9, v147
	s_nop 1
	v_cndmask_b32_e64 v73, 0, 1.0, vcc
	v_cmp_eq_u32_e32 vcc, 10, v147
	s_nop 1
	v_cndmask_b32_e64 v74, 0, 1.0, vcc
	v_cmp_eq_u32_e32 vcc, 11, v147
	s_nop 1
	v_cndmask_b32_e64 v75, 0, 1.0, vcc
	v_cmp_eq_u32_e32 vcc, 12, v147
	s_nop 1
	v_cndmask_b32_e64 v76, 0, 1.0, vcc
	v_cmp_eq_u32_e32 vcc, 13, v147
	s_nop 1
	v_cndmask_b32_e64 v77, 0, 1.0, vcc
	v_cmp_eq_u32_e32 vcc, 14, v147
	s_nop 1
	v_cndmask_b32_e64 v78, 0, 1.0, vcc
	v_cmp_eq_u32_e32 vcc, 15, v147
	s_nop 1
	v_cndmask_b32_e64 v79, 0, 1.0, vcc
	v_cmp_eq_u32_e32 vcc, 16, v147
	s_nop 1
	v_cndmask_b32_e64 v80, 0, 1.0, vcc
	v_cmp_eq_u32_e32 vcc, 17, v147
	s_nop 1
	v_cndmask_b32_e64 v81, 0, 1.0, vcc
	v_cmp_eq_u32_e32 vcc, 18, v147
	s_nop 1
	v_cndmask_b32_e64 v82, 0, 1.0, vcc
	v_cmp_eq_u32_e32 vcc, 19, v147
	s_nop 1
	v_cndmask_b32_e64 v83, 0, 1.0, vcc
	v_cmp_eq_u32_e32 vcc, 20, v147
	s_nop 1
	v_cndmask_b32_e64 v84, 0, 1.0, vcc
	v_cmp_eq_u32_e32 vcc, 21, v147
	s_nop 1
	v_cndmask_b32_e64 v85, 0, 1.0, vcc
	v_cmp_eq_u32_e32 vcc, 22, v147
	s_nop 1
	v_cndmask_b32_e64 v86, 0, 1.0, vcc
	v_cmp_eq_u32_e32 vcc, 23, v147
	s_nop 1
	v_cndmask_b32_e64 v87, 0, 1.0, vcc
	v_cmp_eq_u32_e32 vcc, 24, v147
	s_nop 1
	v_cndmask_b32_e64 v88, 0, 1.0, vcc
	v_cmp_eq_u32_e32 vcc, 25, v147
	s_nop 1
	v_cndmask_b32_e64 v89, 0, 1.0, vcc
	v_cmp_eq_u32_e32 vcc, 26, v147
	s_nop 1
	v_cndmask_b32_e64 v90, 0, 1.0, vcc
	v_cmp_eq_u32_e32 vcc, 27, v147
	s_nop 1
	v_cndmask_b32_e64 v91, 0, 1.0, vcc
	v_cmp_eq_u32_e32 vcc, 28, v147
	s_nop 1
	v_cndmask_b32_e64 v92, 0, 1.0, vcc
	v_cmp_eq_u32_e32 vcc, 29, v147
	s_nop 1
	v_cndmask_b32_e64 v93, 0, 1.0, vcc
	v_cmp_eq_u32_e32 vcc, 30, v147
	s_nop 1
	v_cndmask_b32_e64 v94, 0, 1.0, vcc
	v_cmp_eq_u32_e32 vcc, 31, v147
	s_nop 1
	v_cndmask_b32_e64 v95, 0, 1.0, vcc
	v_cmp_eq_u32_e32 vcc, 32, v147
	s_nop 1
	v_cndmask_b32_e64 v96, 0, 1.0, vcc
	v_cmp_eq_u32_e32 vcc, 33, v147
	s_nop 1
	v_cndmask_b32_e64 v97, 0, 1.0, vcc
	v_cmp_eq_u32_e32 vcc, 34, v147
	s_nop 1
	v_cndmask_b32_e64 v98, 0, 1.0, vcc
	v_cmp_eq_u32_e32 vcc, 35, v147
	s_nop 1
	v_cndmask_b32_e64 v99, 0, 1.0, vcc
	v_cmp_eq_u32_e32 vcc, 36, v147
	s_nop 1
	v_cndmask_b32_e64 v100, 0, 1.0, vcc
	v_cmp_eq_u32_e32 vcc, 37, v147
	s_nop 1
	v_cndmask_b32_e64 v101, 0, 1.0, vcc
	v_cmp_eq_u32_e32 vcc, 38, v147
	s_nop 1
	v_cndmask_b32_e64 v102, 0, 1.0, vcc
	v_cmp_eq_u32_e32 vcc, 39, v147
	s_nop 1
	v_cndmask_b32_e64 v103, 0, 1.0, vcc
	v_cmp_eq_u32_e32 vcc, 40, v147
	s_nop 1
	v_cndmask_b32_e64 v104, 0, 1.0, vcc
	v_cmp_eq_u32_e32 vcc, 41, v147
	s_nop 1
	v_cndmask_b32_e64 v105, 0, 1.0, vcc
	v_cmp_eq_u32_e32 vcc, 42, v147
	s_nop 1
	v_cndmask_b32_e64 v106, 0, 1.0, vcc
	v_cmp_eq_u32_e32 vcc, 43, v147
	s_nop 1
	v_cndmask_b32_e64 v107, 0, 1.0, vcc
	v_cmp_eq_u32_e32 vcc, 44, v147
	s_nop 1
	v_cndmask_b32_e64 v108, 0, 1.0, vcc
	v_cmp_eq_u32_e32 vcc, 45, v147
	s_nop 1
	v_cndmask_b32_e64 v109, 0, 1.0, vcc
	v_cmp_eq_u32_e32 vcc, 46, v147
	s_nop 1
	v_cndmask_b32_e64 v110, 0, 1.0, vcc
	v_cmp_eq_u32_e32 vcc, 47, v147
	s_nop 1
	v_cndmask_b32_e64 v111, 0, 1.0, vcc
	v_cmp_eq_u32_e32 vcc, 48, v147
	s_nop 1
	v_cndmask_b32_e64 v112, 0, 1.0, vcc
	v_cmp_eq_u32_e32 vcc, 49, v147
	s_nop 1
	v_cndmask_b32_e64 v113, 0, 1.0, vcc
	v_cmp_eq_u32_e32 vcc, 50, v147
	s_nop 1
	v_cndmask_b32_e64 v114, 0, 1.0, vcc
	v_cmp_eq_u32_e32 vcc, 51, v147
	s_nop 1
	v_cndmask_b32_e64 v115, 0, 1.0, vcc
	v_cmp_eq_u32_e32 vcc, 52, v147
	s_nop 1
	v_cndmask_b32_e64 v116, 0, 1.0, vcc
	v_cmp_eq_u32_e32 vcc, 53, v147
	s_nop 1
	v_cndmask_b32_e64 v117, 0, 1.0, vcc
	v_cmp_eq_u32_e32 vcc, 54, v147
	s_nop 1
	v_cndmask_b32_e64 v118, 0, 1.0, vcc
	v_cmp_eq_u32_e32 vcc, 55, v147
	s_nop 1
	v_cndmask_b32_e64 v119, 0, 1.0, vcc
	v_cmp_eq_u32_e32 vcc, 56, v147
	s_nop 1
	v_cndmask_b32_e64 v120, 0, 1.0, vcc
	v_cmp_eq_u32_e32 vcc, 57, v147
	s_nop 1
	v_cndmask_b32_e64 v121, 0, 1.0, vcc
	v_cmp_eq_u32_e32 vcc, 58, v147
	s_nop 1
	v_cndmask_b32_e64 v122, 0, 1.0, vcc
	v_cmp_eq_u32_e32 vcc, 59, v147
	s_nop 1
	v_cndmask_b32_e64 v123, 0, 1.0, vcc
	v_cmp_eq_u32_e32 vcc, 60, v147
	s_nop 1
	v_cndmask_b32_e64 v124, 0, 1.0, vcc
	v_cmp_eq_u32_e32 vcc, 61, v147
	s_nop 1
	v_cndmask_b32_e64 v125, 0, 1.0, vcc
	v_cmp_eq_u32_e32 vcc, 62, v147
	s_nop 1
	v_cndmask_b32_e64 v126, 0, 1.0, vcc
	v_cmp_eq_u32_e32 vcc, 63, v147
	s_nop 1
	v_cndmask_b32_e64 v127, 0, 1.0, vcc

; #define SCAN_LOAD(seg) do { _Pragma("unroll") for (int s = 0; s < SB; ++s) { const unsigned st_ = (unsigned)((seg) * SB + s); const unsigned ix = i0 + st_ * DB, fx = f0 + st_ * 3072u; \
;             rg[s][0] = DEC[ix]; rg[s][1] = bf2f(FEAT[fx]); rg[s][2] = bf2f(FEAT[fx + 1024]); rg[s][3] = bf2f(FEAT[fx + 2048]); rg[s][4] = bf2f(AS[ix]); } } while (0)
;     ...
;         for (int seg = 0; seg < CL / SB; ++seg) {
;             const int bi = seg & 1;
;             if (MODE != 2 && seg + 1 < CL / SB) SCAN_LOAD(seg + 1);
;             asm volatile("" ::: "memory");
;     ...
; #pragma unroll 1
;             for (int s = 0; s < (MODE == 1 ? 0 : SB); ++s) {
.LBB0_1065:
	v_cndmask_b32_e64 v130, 0, 1, s[64:65]
	v_mul_lo_u32 v130, v130, s40
	v_add_u32_e32 v158, v151, v130
	s_mov_b32 s45, 0
	s_and_b32 s90, s43, 15
	s_cmp_lg_u32 s90, 0
	s_cbranch_scc1 .Lp5_norenorm
	s_cmp_eq_u32 s43, 0
	s_cbranch_scc1 .Lp5_norenorm
	v_add_u32_e32 v130, v151, v245
	ds_write_b32 v130, v246 offset:12288
	v_and_b32_e32 v255, 0xc0, v245
	v_add_u32_e32 v255, v255, v151
	ds_read_b128 v[192:195], v255 offset:12288
	ds_read_b128 v[196:199], v255 offset:12304
	ds_read_b128 v[200:203], v255 offset:12320
	ds_read_b128 v[204:207], v255 offset:12336
	s_waitcnt lgkmcnt(0)
	v_mul_f32_e32 v0, v0, v192
	v_mul_f32_e32 v64, v64, v192
	v_mul_f32_e32 v1, v1, v192
	v_mul_f32_e32 v65, v65, v192
	v_mul_f32_e32 v2, v2, v192
	v_mul_f32_e32 v66, v66, v192
	v_mul_f32_e32 v3, v3, v192
	v_mul_f32_e32 v67, v67, v192
	v_mul_f32_e32 v4, v4, v193
	v_mul_f32_e32 v68, v68, v193
	v_mul_f32_e32 v5, v5, v193
	v_mul_f32_e32 v69, v69, v193
	v_mul_f32_e32 v6, v6, v193
	v_mul_f32_e32 v70, v70, v193
	v_mul_f32_e32 v7, v7, v193
	v_mul_f32_e32 v71, v71, v193
	v_mul_f32_e32 v8, v8, v194
	v_mul_f32_e32 v72, v72, v194
	v_mul_f32_e32 v9, v9, v194
	v_mul_f32_e32 v73, v73, v194
	v_mul_f32_e32 v10, v10, v194
	v_mul_f32_e32 v74, v74, v194
	v_mul_f32_e32 v11, v11, v194
	v_mul_f32_e32 v75, v75, v194
	v_mul_f32_e32 v12, v12, v195
	v_mul_f32_e32 v76, v76, v195
	v_mul_f32_e32 v13, v13, v195
	v_mul_f32_e32 v77, v77, v195
	v_mul_f32_e32 v14, v14, v195
	v_mul_f32_e32 v78, v78, v195
	v_mul_f32_e32 v15, v15, v195
	v_mul_f32_e32 v79, v79, v195
	v_mul_f32_e32 v16, v16, v196
	v_mul_f32_e32 v80, v80, v196
	v_mul_f32_e32 v17, v17, v196
	v_mul_f32_e32 v81, v81, v196
	v_mul_f32_e32 v18, v18, v196
	v_mul_f32_e32 v82, v82, v196
	v_mul_f32_e32 v19, v19, v196
	v_mul_f32_e32 v83, v83, v196
	v_mul_f32_e32 v20, v20, v197
	v_mul_f32_e32 v84, v84, v197
	v_mul_f32_e32 v21, v21, v197
	v_mul_f32_e32 v85, v85, v197
	v_mul_f32_e32 v22, v22, v197
	v_mul_f32_e32 v86, v86, v197
	v_mul_f32_e32 v23, v23, v197
	v_mul_f32_e32 v87, v87, v197
	v_mul_f32_e32 v24, v24, v198
	v_mul_f32_e32 v88, v88, v198
	v_mul_f32_e32 v25, v25, v198
	v_mul_f32_e32 v89, v89, v198
	v_mul_f32_e32 v26, v26, v198
	v_mul_f32_e32 v90, v90, v198
	v_mul_f32_e32 v27, v27, v198
	v_mul_f32_e32 v91, v91, v198
	v_mul_f32_e32 v28, v28, v199
	v_mul_f32_e32 v92, v92, v199
	v_mul_f32_e32 v29, v29, v199
	v_mul_f32_e32 v93, v93, v199
	v_mul_f32_e32 v30, v30, v199
	v_mul_f32_e32 v94, v94, v199
	v_mul_f32_e32 v31, v31, v199
	v_mul_f32_e32 v95, v95, v199
	v_mul_f32_e32 v32, v32, v200
	v_mul_f32_e32 v96, v96, v200
	v_mul_f32_e32 v33, v33, v200
	v_mul_f32_e32 v97, v97, v200
	v_mul_f32_e32 v34, v34, v200
	v_mul_f32_e32 v98, v98, v200
	v_mul_f32_e32 v35, v35, v200
	v_mul_f32_e32 v99, v99, v200
	v_mul_f32_e32 v36, v36, v201
	v_mul_f32_e32 v100, v100, v201
	v_mul_f32_e32 v37, v37, v201
	v_mul_f32_e32 v101, v101, v201
	v_mul_f32_e32 v38, v38, v201
	v_mul_f32_e32 v102, v102, v201
	v_mul_f32_e32 v39, v39, v201
	v_mul_f32_e32 v103, v103, v201
	v_mul_f32_e32 v40, v40, v202
	v_mul_f32_e32 v104, v104, v202
	v_mul_f32_e32 v41, v41, v202
	v_mul_f32_e32 v105, v105, v202
	v_mul_f32_e32 v42, v42, v202
	v_mul_f32_e32 v106, v106, v202
	v_mul_f32_e32 v43, v43, v202
	v_mul_f32_e32 v107, v107, v202
	v_mul_f32_e32 v44, v44, v203
	v_mul_f32_e32 v108, v108, v203
	v_mul_f32_e32 v45, v45, v203
	v_mul_f32_e32 v109, v109, v203
	v_mul_f32_e32 v46, v46, v203
	v_mul_f32_e32 v110, v110, v203
	v_mul_f32_e32 v47, v47, v203
	v_mul_f32_e32 v111, v111, v203
	v_mul_f32_e32 v48, v48, v204
	v_mul_f32_e32 v112, v112, v204
	v_mul_f32_e32 v49, v49, v204
	v_mul_f32_e32 v113, v113, v204
	v_mul_f32_e32 v50, v50, v204
	v_mul_f32_e32 v114, v114, v204
	v_mul_f32_e32 v51, v51, v204
	v_mul_f32_e32 v115, v115, v204
	v_mul_f32_e32 v52, v52, v205
	v_mul_f32_e32 v116, v116, v205
	v_mul_f32_e32 v53, v53, v205
	v_mul_f32_e32 v117, v117, v205
	v_mul_f32_e32 v54, v54, v205
	v_mul_f32_e32 v118, v118, v205
	v_mul_f32_e32 v55, v55, v205
	v_mul_f32_e32 v119, v119, v205
	v_mul_f32_e32 v56, v56, v206
	v_mul_f32_e32 v120, v120, v206
	v_mul_f32_e32 v57, v57, v206
	v_mul_f32_e32 v121, v121, v206
	v_mul_f32_e32 v58, v58, v206
	v_mul_f32_e32 v122, v122, v206
	v_mul_f32_e32 v59, v59, v206
	v_mul_f32_e32 v123, v123, v206
	v_mul_f32_e32 v60, v60, v207
	v_mul_f32_e32 v124, v124, v207
	v_mul_f32_e32 v61, v61, v207
	v_mul_f32_e32 v125, v125, v207
	v_mul_f32_e32 v62, v62, v207
	v_mul_f32_e32 v126, v126, v207
	v_mul_f32_e32 v63, v63, v207
	v_mul_f32_e32 v127, v127, v207
	v_mov_b32_e32 v246, 1.0
; #define LAS __attribute__((address_space(3)))
;     ...
;                 const LAS float* sv = buf + ((bi * SB + s) * NV) * 64;
;                 const LAS f32x4* L4 = (const LAS f32x4*)sv;
;                 f32x2 qloa = {0.f, 0.f}, qhia = qloa, qlob = qloa, qhib = qloa, plo = qloa, phi = qloa, yloa = qloa, yhia = qloa, ylob = qloa, yhib = qloa, saq2 = qloa, sap2 = qloa;
;                 const float vv = sv[4 * 64 + lane]; const f32x2 vv2 = {vv, vv};
;                 const float xk = sv[1 * 64 + lane], xb = sv[2 * 64 + lane], xr = sv[5 * 64 + lane];
;                 float qd0 = 0.f, qd1 = 0.f, qd2 = 0.f, qd3 = 0.f, pd0 = 0.f, pd1 = 0.f, pd2 = 0.f, pd3 = 0.f, yd0 = 0.f, yd1 = 0.f, yd2 = 0.f, yd3 = 0.f, zd0 = 0.f, zd1 = 0.f, zd2 = 0.f, zd3 = 0.f;
;                 const int l15 = lane & 15; float xkq0 = sv[64 + l15], xkq1 = sv[64 + 16 + l15], xkq2 = sv[64 + 32 + l15], xkq3 = sv[64 + 48 + l15], xrq0 = sv[320 + l15], xrq1 = sv[320 + 16 + l15], xrq2 = sv[320 + 32 + l15], xrq3 = sv[320 + 48 + l15];
;     ...
;                 DPPFMAC(qd0, xkq0, Q2[0].x, 0); DPPFMAC(pd0, xkq0, P2[0].x, 0);
;                 DPPFMAC(qd1, xkq0, Q2[0].y, 1); DPPFMAC(pd1, xkq0, P2[0].y, 1);
;                 DPPFMAC(qd2, xkq0, Q2[1].x, 2); DPPFMAC(pd2, xkq0, P2[1].x, 2);
;                 DPPFMAC(qd3, xkq0, Q2[1].y, 3); DPPFMAC(pd3, xkq0, P2[1].y, 3);
;                 DPPFMAC(qd0, xkq0, Q2[2].x, 4); DPPFMAC(pd0, xkq0, P2[2].x, 4);
;                 DPPFMAC(qd1, xkq0, Q2[2].y, 5); DPPFMAC(pd1, xkq0, P2[2].y, 5);
;                 DPPFMAC(qd2, xkq0, Q2[3].x, 6); DPPFMAC(pd2, xkq0, P2[3].x, 6);
;                 DPPFMAC(qd3, xkq0, Q2[3].y, 7); DPPFMAC(pd3, xkq0, P2[3].y, 7);
;                 DPPFMAC(qd0, xkq0, Q2[4].x, 8); DPPFMAC(pd0, xkq0, P2[4].x, 8);
;                 DPPFMAC(qd1, xkq0, Q2[4].y, 9); DPPFMAC(pd1, xkq0, P2[4].y, 9);
;                 DPPFMAC(qd2, xkq0, Q2[5].x, 10); DPPFMAC(pd2, xkq0, P2[5].x, 10);
;                 DPPFMAC(qd3, xkq0, Q2[5].y, 11); DPPFMAC(pd3, xkq0, P2[5].y, 11);
;                 DPPFMAC(qd0, xkq0, Q2[6].x, 12); DPPFMAC(pd0, xkq0, P2[6].x, 12);
;                 DPPFMAC(qd1, xkq0, Q2[6].y, 13); DPPFMAC(pd1, xkq0, P2[6].y, 13);
;                 DPPFMAC(qd2, xkq0, Q2[7].x, 14); DPPFMAC(pd2, xkq0, P2[7].x, 14);
;                 DPPFMAC(qd3, xkq0, Q2[7].y, 15); DPPFMAC(pd3, xkq0, P2[7].y, 15);
;                 __builtin_amdgcn_sched_barrier(0);
.Lp5_norenorm:
.Lp5_step:
	v_and_b32_e32 v255, 0xc0, v245
	v_add_u32_e32 v255, v255, v158
	v_add_u32_e32 v130, v245, v158
	ds_read_b32 v216, v130 offset:0
	ds_read_b32 v217, v130 offset:256
	ds_read_b32 v218, v130 offset:512
	ds_read_b32 v219, v130 offset:768
	ds_read_b32 v220, v130 offset:1280
	ds_read_b32 v254, v130 offset:1024
	s_waitcnt lgkmcnt(0)
	v_mul_f32_e32 v217, v217, v246
	v_mul_f32_e32 v246, v246, v216
	v_rcp_f32_e32 v221, v246
	v_mul_f32_e32 v220, v220, v246
	ds_write_b32 v130, v217 offset:256
	v_mul_f32_e32 v218, v218, v221
	v_mul_f32_e32 v219, v219, v221
	ds_write_b32 v130, v220 offset:1280
	ds_write_b32 v130, v218 offset:512
	ds_write_b32 v130, v219 offset:768
	ds_read_b128 v[192:195], v255 offset:256
	ds_read_b128 v[196:199], v255 offset:272
	ds_read_b128 v[200:203], v255 offset:288
	ds_read_b128 v[204:207], v255 offset:304
	ds_read_b128 v[224:227], v255 offset:512
	ds_read_b128 v[228:231], v255 offset:528
	ds_read_b128 v[232:235], v255 offset:544
	ds_read_b128 v[236:239], v255 offset:560
	s_waitcnt lgkmcnt(4)
	ds_read_b128 v[240:243], v255 offset:768
	ds_read_b128 v[166:169], v255 offset:784
	ds_read_b128 v[170:173], v255 offset:800
	ds_read_b128 v[174:177], v255 offset:816
	v_mul_f32_e32 v208, v0, v192
	v_mul_f32_e32 v212, v64, v192
	v_mul_f32_e32 v209, v1, v192
	v_mul_f32_e32 v213, v65, v192
	v_mul_f32_e32 v210, v2, v192
	v_mul_f32_e32 v214, v66, v192
	v_mul_f32_e32 v211, v3, v192
	v_mul_f32_e32 v215, v67, v192
	v_fmac_f32_e32 v208, v4, v193
	v_fmac_f32_e32 v212, v68, v193
	v_fmac_f32_e32 v209, v5, v193
	v_fmac_f32_e32 v213, v69, v193
	v_fmac_f32_e32 v210, v6, v193
	v_fmac_f32_e32 v214, v70, v193
	v_fmac_f32_e32 v211, v7, v193
	v_fmac_f32_e32 v215, v71, v193
	v_fmac_f32_e32 v208, v8, v194
	v_fmac_f32_e32 v212, v72, v194
	v_fmac_f32_e32 v209, v9, v194
	v_fmac_f32_e32 v213, v73, v194
	v_fmac_f32_e32 v210, v10, v194
	v_fmac_f32_e32 v214, v74, v194
	v_fmac_f32_e32 v211, v11, v194
	v_fmac_f32_e32 v215, v75, v194
	v_fmac_f32_e32 v208, v12, v195
	v_fmac_f32_e32 v212, v76, v195
	v_fmac_f32_e32 v209, v13, v195
	v_fmac_f32_e32 v213, v77, v195
	v_fmac_f32_e32 v210, v14, v195
	v_fmac_f32_e32 v214, v78, v195
	v_fmac_f32_e32 v211, v15, v195
	v_fmac_f32_e32 v215, v79, v195
	v_fmac_f32_e32 v208, v16, v196
	v_fmac_f32_e32 v212, v80, v196
	v_fmac_f32_e32 v209, v17, v196
	v_fmac_f32_e32 v213, v81, v196
	v_fmac_f32_e32 v210, v18, v196
	v_fmac_f32_e32 v214, v82, v196
	v_fmac_f32_e32 v211, v19, v196
	v_fmac_f32_e32 v215, v83, v196
	v_fmac_f32_e32 v208, v20, v197
	v_fmac_f32_e32 v212, v84, v197
	v_fmac_f32_e32 v209, v21, v197
	v_fmac_f32_e32 v213, v85, v197
	v_fmac_f32_e32 v210, v22, v197
	v_fmac_f32_e32 v214, v86, v197
	v_fmac_f32_e32 v211, v23, v197
	v_fmac_f32_e32 v215, v87, v197
	v_fmac_f32_e32 v208, v24, v198
	v_fmac_f32_e32 v212, v88, v198
	v_fmac_f32_e32 v209, v25, v198
	v_fmac_f32_e32 v213, v89, v198
	v_fmac_f32_e32 v210, v26, v198
	v_fmac_f32_e32 v214, v90, v198
	v_fmac_f32_e32 v211, v27, v198
	v_fmac_f32_e32 v215, v91, v198
	v_fmac_f32_e32 v208, v28, v199
	v_fmac_f32_e32 v212, v92, v199
	v_fmac_f32_e32 v209, v29, v199
	v_fmac_f32_e32 v213, v93, v199
	v_fmac_f32_e32 v210, v30, v199
	v_fmac_f32_e32 v214, v94, v199
	v_fmac_f32_e32 v211, v31, v199
	v_fmac_f32_e32 v215, v95, v199
	v_fmac_f32_e32 v208, v32, v200
	v_fmac_f32_e32 v212, v96, v200
	v_fmac_f32_e32 v209, v33, v200
	v_fmac_f32_e32 v213, v97, v200
	v_fmac_f32_e32 v210, v34, v200
	v_fmac_f32_e32 v214, v98, v200
	v_fmac_f32_e32 v211, v35, v200
	v_fmac_f32_e32 v215, v99, v200
	v_fmac_f32_e32 v208, v36, v201
	v_fmac_f32_e32 v212, v100, v201
	v_fmac_f32_e32 v209, v37, v201
	v_fmac_f32_e32 v213, v101, v201
	v_fmac_f32_e32 v210, v38, v201
	v_fmac_f32_e32 v214, v102, v201
	v_fmac_f32_e32 v211, v39, v201
	v_fmac_f32_e32 v215, v103, v201
	v_fmac_f32_e32 v208, v40, v202
	v_fmac_f32_e32 v212, v104, v202
	v_fmac_f32_e32 v209, v41, v202
	v_fmac_f32_e32 v213, v105, v202
	v_fmac_f32_e32 v210, v42, v202
	v_fmac_f32_e32 v214, v106, v202
	v_fmac_f32_e32 v211, v43, v202
	v_fmac_f32_e32 v215, v107, v202
	v_fmac_f32_e32 v208, v44, v203
	v_fmac_f32_e32 v212, v108, v203
	v_fmac_f32_e32 v209, v45, v203
	v_fmac_f32_e32 v213, v109, v203
	v_fmac_f32_e32 v210, v46, v203
	v_fmac_f32_e32 v214, v110, v203
	v_fmac_f32_e32 v211, v47, v203
	v_fmac_f32_e32 v215, v111, v203
	v_fmac_f32_e32 v208, v48, v204
	v_fmac_f32_e32 v212, v112, v204
	v_fmac_f32_e32 v209, v49, v204
	v_fmac_f32_e32 v213, v113, v204
	v_fmac_f32_e32 v210, v50, v204
	v_fmac_f32_e32 v214, v114, v204
	v_fmac_f32_e32 v211, v51, v204
	v_fmac_f32_e32 v215, v115, v204
	v_fmac_f32_e32 v208, v52, v205
	v_fmac_f32_e32 v212, v116, v205
	v_fmac_f32_e32 v209, v53, v205
	v_fmac_f32_e32 v213, v117, v205
	v_fmac_f32_e32 v210, v54, v205
	v_fmac_f32_e32 v214, v118, v205
	v_fmac_f32_e32 v211, v55, v205
	v_fmac_f32_e32 v215, v119, v205
	v_fmac_f32_e32 v208, v56, v206
	v_fmac_f32_e32 v212, v120, v206
	v_fmac_f32_e32 v209, v57, v206
	v_fmac_f32_e32 v213, v121, v206
	v_fmac_f32_e32 v210, v58, v206
	v_fmac_f32_e32 v214, v122, v206
	v_fmac_f32_e32 v211, v59, v206
	v_fmac_f32_e32 v215, v123, v206
	v_fmac_f32_e32 v208, v60, v207
	v_fmac_f32_e32 v212, v124, v207
	v_fmac_f32_e32 v209, v61, v207
	v_fmac_f32_e32 v213, v125, v207
	v_fmac_f32_e32 v210, v62, v207
	v_fmac_f32_e32 v214, v126, v207
	v_fmac_f32_e32 v211, v63, v207
	v_fmac_f32_e32 v215, v127, v207
	v_add_f32_dpp v208, v208, v208 quad_perm:[1,0,3,2] row_mask:0xf bank_mask:0xf
	v_add_f32_dpp v209, v209, v209 quad_perm:[1,0,3,2] row_mask:0xf bank_mask:0xf
	v_add_f32_dpp v210, v210, v210 quad_perm:[1,0,3,2] row_mask:0xf bank_mask:0xf
	v_add_f32_dpp v211, v211, v211 quad_perm:[1,0,3,2] row_mask:0xf bank_mask:0xf
	v_add_f32_dpp v212, v212, v212 quad_perm:[1,0,3,2] row_mask:0xf bank_mask:0xf
	v_add_f32_dpp v213, v213, v213 quad_perm:[1,0,3,2] row_mask:0xf bank_mask:0xf
	v_add_f32_dpp v214, v214, v214 quad_perm:[1,0,3,2] row_mask:0xf bank_mask:0xf
	v_add_f32_dpp v215, v215, v215 quad_perm:[1,0,3,2] row_mask:0xf bank_mask:0xf
	v_add_f32_dpp v208, v208, v208 quad_perm:[2,3,0,1] row_mask:0xf bank_mask:0xf
	v_add_f32_dpp v209, v209, v209 quad_perm:[2,3,0,1] row_mask:0xf bank_mask:0xf
	v_add_f32_dpp v210, v210, v210 quad_perm:[2,3,0,1] row_mask:0xf bank_mask:0xf
	v_add_f32_dpp v211, v211, v211 quad_perm:[2,3,0,1] row_mask:0xf bank_mask:0xf
	v_add_f32_dpp v212, v212, v212 quad_perm:[2,3,0,1] row_mask:0xf bank_mask:0xf
	v_add_f32_dpp v213, v213, v213 quad_perm:[2,3,0,1] row_mask:0xf bank_mask:0xf
	v_add_f32_dpp v214, v214, v214 quad_perm:[2,3,0,1] row_mask:0xf bank_mask:0xf
	v_add_f32_dpp v215, v215, v215 quad_perm:[2,3,0,1] row_mask:0xf bank_mask:0xf
	v_cndmask_b32_e64 v178, -v208, -v209, s[86:87]
	v_cndmask_b32_e64 v179, -v212, -v213, s[86:87]
	v_cndmask_b32_e64 v178, v178, -v210, s[88:89]
	v_cndmask_b32_e64 v179, v179, -v214, s[88:89]
	v_cndmask_b32_e64 v178, v178, -v211, s[84:85]
	v_cndmask_b32_e64 v179, v179, -v215, s[84:85]
	s_waitcnt lgkmcnt(0)
;     ...
;                 { const f32x2 bxy = b_0.xy, bzw = b_0.zw;
;                 Q2[0] = Q2[0] * d_0.xy + (saq2 * bxy + vv2 * k_0.xy); Q2[1] = Q2[1] * d_0.zw + (saq2 * bzw + vv2 * k_0.zw);
;                 P2[0] = P2[0] * d_0.xy + sap2 * bxy; P2[1] = P2[1] * d_0.zw + sap2 * bzw;
;                 DPPFMAC(yd0, xrq0, Q2[0].x, 0); DPPFMAC(zd0, xrq0, P2[0].x, 0);
;                 DPPFMAC(yd1, xrq0, Q2[0].y, 1); DPPFMAC(zd1, xrq0, P2[0].y, 1);
;                 DPPFMAC(yd2, xrq0, Q2[1].x, 2); DPPFMAC(zd2, xrq0, P2[1].x, 2);
;                 DPPFMAC(yd3, xrq0, Q2[1].y, 3); DPPFMAC(zd3, xrq0, P2[1].y, 3);
;                 }
;                 { const f32x2 bxy = b_1.xy, bzw = b_1.zw;
;                 Q2[2] = Q2[2] * d_1.xy + (saq2 * bxy + vv2 * k_1.xy); Q2[3] = Q2[3] * d_1.zw + (saq2 * bzw + vv2 * k_1.zw);
;                 P2[2] = P2[2] * d_1.xy + sap2 * bxy; P2[3] = P2[3] * d_1.zw + sap2 * bzw;
;                 DPPFMAC(yd0, xrq0, Q2[2].x, 4); DPPFMAC(zd0, xrq0, P2[2].x, 4);
;                 DPPFMAC(yd1, xrq0, Q2[2].y, 5); DPPFMAC(zd1, xrq0, P2[2].y, 5);
;                 DPPFMAC(yd2, xrq0, Q2[3].x, 6); DPPFMAC(zd2, xrq0, P2[3].x, 6);
;                 DPPFMAC(yd3, xrq0, Q2[3].y, 7); DPPFMAC(zd3, xrq0, P2[3].y, 7);
;                 }
;                 __builtin_amdgcn_sched_barrier(0);
;                 f32x4 d_4 = L4[4], b_4 = L4[36], k_4 = L4[52];
;                 f32x4 d_5 = L4[5], b_5 = L4[37], k_5 = L4[53];
;                 { const f32x2 bxy = b_2.xy, bzw = b_2.zw;
;                 Q2[4] = Q2[4] * d_2.xy + (saq2 * bxy + vv2 * k_2.xy); Q2[5] = Q2[5] * d_2.zw + (saq2 * bzw + vv2 * k_2.zw);
;                 P2[4] = P2[4] * d_2.xy + sap2 * bxy; P2[5] = P2[5] * d_2.zw + sap2 * bzw;
;                 DPPFMAC(yd0, xrq0, Q2[4].x, 8); DPPFMAC(zd0, xrq0, P2[4].x, 8);
;                 DPPFMAC(yd1, xrq0, Q2[4].y, 9); DPPFMAC(zd1, xrq0, P2[4].y, 9);
;                 DPPFMAC(yd2, xrq0, Q2[5].x, 10); DPPFMAC(zd2, xrq0, P2[5].x, 10);
;                 DPPFMAC(yd3, xrq0, Q2[5].y, 11); DPPFMAC(zd3, xrq0, P2[5].y, 11);
;                 }
;                 { const f32x2 bxy = b_3.xy, bzw = b_3.zw;
;                 Q2[6] = Q2[6] * d_3.xy + (saq2 * bxy + vv2 * k_3.xy); Q2[7] = Q2[7] * d_3.zw + (saq2 * bzw + vv2 * k_3.zw);
;                 P2[6] = P2[6] * d_3.xy + sap2 * bxy; P2[7] = P2[7] * d_3.zw + sap2 * bzw;
	ds_read_b128 v[192:195], v255 offset:1280
	ds_read_b128 v[196:199], v255 offset:1296
	ds_read_b128 v[200:203], v255 offset:1312
	ds_read_b128 v[204:207], v255 offset:1328
	v_mfma_f32_4x4x1_16b_f32 v[0:3], v178, v224, v[0:3]
	v_mfma_f32_4x4x1_16b_f32 v[64:67], v179, v224, v[64:67]
	v_mfma_f32_4x4x1_16b_f32 v[4:7], v178, v225, v[4:7]
	v_mfma_f32_4x4x1_16b_f32 v[68:71], v179, v225, v[68:71]
	v_mfma_f32_4x4x1_16b_f32 v[0:3], v254, v240, v[0:3]
	v_mfma_f32_4x4x1_16b_f32 v[8:11], v178, v226, v[8:11]
	v_mfma_f32_4x4x1_16b_f32 v[72:75], v179, v226, v[72:75]
	v_mfma_f32_4x4x1_16b_f32 v[4:7], v254, v241, v[4:7]
	s_waitcnt lgkmcnt(0)
	v_mfma_f32_4x4x1_16b_f32 v[12:15], v178, v227, v[12:15]
	v_mul_f32_e32 v208, v0, v192
	v_mul_f32_e32 v212, v64, v192
	v_mul_f32_e32 v209, v1, v192
	v_mul_f32_e32 v213, v65, v192
	v_mfma_f32_4x4x1_16b_f32 v[76:79], v179, v227, v[76:79]
	v_mul_f32_e32 v210, v2, v192
	v_mul_f32_e32 v214, v66, v192
	v_mul_f32_e32 v211, v3, v192
	v_mul_f32_e32 v215, v67, v192
	v_mfma_f32_4x4x1_16b_f32 v[8:11], v254, v242, v[8:11]
	v_mfma_f32_4x4x1_16b_f32 v[16:19], v178, v228, v[16:19]
	v_fmac_f32_e32 v208, v4, v193
	v_fmac_f32_e32 v212, v68, v193
	v_fmac_f32_e32 v209, v5, v193
	v_fmac_f32_e32 v213, v69, v193
	v_mfma_f32_4x4x1_16b_f32 v[80:83], v179, v228, v[80:83]
	v_fmac_f32_e32 v210, v6, v193
	v_fmac_f32_e32 v214, v70, v193
	v_fmac_f32_e32 v211, v7, v193
	v_fmac_f32_e32 v215, v71, v193
	v_mfma_f32_4x4x1_16b_f32 v[12:15], v254, v243, v[12:15]
	v_mfma_f32_4x4x1_16b_f32 v[20:23], v178, v229, v[20:23]
	v_fmac_f32_e32 v208, v8, v194
	v_fmac_f32_e32 v212, v72, v194
	v_fmac_f32_e32 v209, v9, v194
	v_fmac_f32_e32 v213, v73, v194
	v_mfma_f32_4x4x1_16b_f32 v[84:87], v179, v229, v[84:87]
	v_fmac_f32_e32 v210, v10, v194
	v_fmac_f32_e32 v214, v74, v194
	v_fmac_f32_e32 v211, v11, v194
	v_fmac_f32_e32 v215, v75, v194
	v_mfma_f32_4x4x1_16b_f32 v[16:19], v254, v166, v[16:19]
	v_mfma_f32_4x4x1_16b_f32 v[24:27], v178, v230, v[24:27]
	v_fmac_f32_e32 v208, v12, v195
	v_fmac_f32_e32 v212, v76, v195
	v_fmac_f32_e32 v209, v13, v195
	v_fmac_f32_e32 v213, v77, v195
	v_mfma_f32_4x4x1_16b_f32 v[88:91], v179, v230, v[88:91]
	v_fmac_f32_e32 v210, v14, v195
	v_fmac_f32_e32 v214, v78, v195
	v_fmac_f32_e32 v211, v15, v195
	v_fmac_f32_e32 v215, v79, v195
	v_mfma_f32_4x4x1_16b_f32 v[20:23], v254, v167, v[20:23]
	v_mfma_f32_4x4x1_16b_f32 v[28:31], v178, v231, v[28:31]
	v_fmac_f32_e32 v208, v16, v196
	v_fmac_f32_e32 v212, v80, v196
	v_fmac_f32_e32 v209, v17, v196
	v_fmac_f32_e32 v213, v81, v196
	v_mfma_f32_4x4x1_16b_f32 v[92:95], v179, v231, v[92:95]
	v_fmac_f32_e32 v210, v18, v196
	v_fmac_f32_e32 v214, v82, v196
	v_fmac_f32_e32 v211, v19, v196
	v_fmac_f32_e32 v215, v83, v196
	v_mfma_f32_4x4x1_16b_f32 v[24:27], v254, v168, v[24:27]
	v_mfma_f32_4x4x1_16b_f32 v[32:35], v178, v232, v[32:35]
	v_fmac_f32_e32 v208, v20, v197
	v_fmac_f32_e32 v212, v84, v197
	v_fmac_f32_e32 v209, v21, v197
	v_fmac_f32_e32 v213, v85, v197
	v_mfma_f32_4x4x1_16b_f32 v[96:99], v179, v232, v[96:99]
	v_fmac_f32_e32 v210, v22, v197
	v_fmac_f32_e32 v214, v86, v197
	v_fmac_f32_e32 v211, v23, v197
	v_fmac_f32_e32 v215, v87, v197
	v_mfma_f32_4x4x1_16b_f32 v[28:31], v254, v169, v[28:31]
	v_mfma_f32_4x4x1_16b_f32 v[36:39], v178, v233, v[36:39]
	v_fmac_f32_e32 v208, v24, v198
	v_fmac_f32_e32 v212, v88, v198
	v_fmac_f32_e32 v209, v25, v198
	v_fmac_f32_e32 v213, v89, v198
	v_mfma_f32_4x4x1_16b_f32 v[100:103], v179, v233, v[100:103]
	v_fmac_f32_e32 v210, v26, v198
	v_fmac_f32_e32 v214, v90, v198
	v_fmac_f32_e32 v211, v27, v198
	v_fmac_f32_e32 v215, v91, v198
	v_mfma_f32_4x4x1_16b_f32 v[32:35], v254, v170, v[32:35]
	v_mfma_f32_4x4x1_16b_f32 v[40:43], v178, v234, v[40:43]
	v_fmac_f32_e32 v208, v28, v199
	v_fmac_f32_e32 v212, v92, v199
	v_fmac_f32_e32 v209, v29, v199
	v_fmac_f32_e32 v213, v93, v199
	v_mfma_f32_4x4x1_16b_f32 v[104:107], v179, v234, v[104:107]
	v_fmac_f32_e32 v210, v30, v199
	v_fmac_f32_e32 v214, v94, v199
	v_fmac_f32_e32 v211, v31, v199
	v_fmac_f32_e32 v215, v95, v199
	v_mfma_f32_4x4x1_16b_f32 v[36:39], v254, v171, v[36:39]
	v_mfma_f32_4x4x1_16b_f32 v[44:47], v178, v235, v[44:47]
	v_fmac_f32_e32 v208, v32, v200
	v_fmac_f32_e32 v212, v96, v200
	v_fmac_f32_e32 v209, v33, v200
	v_fmac_f32_e32 v213, v97, v200
	v_mfma_f32_4x4x1_16b_f32 v[108:111], v179, v235, v[108:111]
	v_fmac_f32_e32 v210, v34, v200
	v_fmac_f32_e32 v214, v98, v200
	v_fmac_f32_e32 v211, v35, v200
	v_fmac_f32_e32 v215, v99, v200
	v_mfma_f32_4x4x1_16b_f32 v[40:43], v254, v172, v[40:43]
	v_mfma_f32_4x4x1_16b_f32 v[48:51], v178, v236, v[48:51]
	v_fmac_f32_e32 v208, v36, v201
	v_fmac_f32_e32 v212, v100, v201
	v_fmac_f32_e32 v209, v37, v201
	v_fmac_f32_e32 v213, v101, v201
	v_mfma_f32_4x4x1_16b_f32 v[112:115], v179, v236, v[112:115]
	v_fmac_f32_e32 v210, v38, v201
	v_fmac_f32_e32 v214, v102, v201
	v_fmac_f32_e32 v211, v39, v201
	v_fmac_f32_e32 v215, v103, v201
	v_mfma_f32_4x4x1_16b_f32 v[44:47], v254, v173, v[44:47]
	v_mfma_f32_4x4x1_16b_f32 v[52:55], v178, v237, v[52:55]
	v_fmac_f32_e32 v208, v40, v202
	v_fmac_f32_e32 v212, v104, v202
	v_fmac_f32_e32 v209, v41, v202
	v_fmac_f32_e32 v213, v105, v202
	v_mfma_f32_4x4x1_16b_f32 v[116:119], v179, v237, v[116:119]
	v_fmac_f32_e32 v210, v42, v202
	v_fmac_f32_e32 v214, v106, v202
	v_fmac_f32_e32 v211, v43, v202
	v_fmac_f32_e32 v215, v107, v202
	v_mfma_f32_4x4x1_16b_f32 v[48:51], v254, v174, v[48:51]
	v_mfma_f32_4x4x1_16b_f32 v[56:59], v178, v238, v[56:59]
	v_fmac_f32_e32 v208, v44, v203
	v_fmac_f32_e32 v212, v108, v203
	v_fmac_f32_e32 v209, v45, v203
	v_fmac_f32_e32 v213, v109, v203
	v_mfma_f32_4x4x1_16b_f32 v[120:123], v179, v238, v[120:123]
	v_fmac_f32_e32 v210, v46, v203
	v_fmac_f32_e32 v214, v110, v203
;     ...
;                 { const f32x2 bxy = b_10.xy, bzw = b_10.zw;
;                 Q2[20] = Q2[20] * d_10.xy + (saq2 * bxy + vv2 * k_10.xy); Q2[21] = Q2[21] * d_10.zw + (saq2 * bzw + vv2 * k_10.zw);
;                 P2[20] = P2[20] * d_10.xy + sap2 * bxy; P2[21] = P2[21] * d_10.zw + sap2 * bzw;
;                 DPPFMAC(yd0, xrq2, Q2[20].x, 8); DPPFMAC(zd0, xrq2, P2[20].x, 8);
;                 DPPFMAC(yd1, xrq2, Q2[20].y, 9); DPPFMAC(zd1, xrq2, P2[20].y, 9);
;                 DPPFMAC(yd2, xrq2, Q2[21].x, 10); DPPFMAC(zd2, xrq2, P2[21].x, 10);
;                 DPPFMAC(yd3, xrq2, Q2[21].y, 11); DPPFMAC(zd3, xrq2, P2[21].y, 11);
;                 }
;                 { const f32x2 bxy = b_11.xy, bzw = b_11.zw;
;                 Q2[22] = Q2[22] * d_11.xy + (saq2 * bxy + vv2 * k_11.xy); Q2[23] = Q2[23] * d_11.zw + (saq2 * bzw + vv2 * k_11.zw);
;                 P2[22] = P2[22] * d_11.xy + sap2 * bxy; P2[23] = P2[23] * d_11.zw + sap2 * bzw;
;                 DPPFMAC(yd0, xrq2, Q2[22].x, 12); DPPFMAC(zd0, xrq2, P2[22].x, 12);
;                 DPPFMAC(yd1, xrq2, Q2[22].y, 13); DPPFMAC(zd1, xrq2, P2[22].y, 13);
;                 DPPFMAC(yd2, xrq2, Q2[23].x, 14); DPPFMAC(zd2, xrq2, P2[23].x, 14);
;                 DPPFMAC(yd3, xrq2, Q2[23].y, 15); DPPFMAC(zd3, xrq2, P2[23].y, 15);
;                 }
;                 __builtin_amdgcn_sched_barrier(0);
;                 f32x4 d_14 = L4[14], b_14 = L4[46], k_14 = L4[62];
;                 f32x4 d_15 = L4[15], b_15 = L4[47], k_15 = L4[63];
;                 { const f32x2 bxy = b_12.xy, bzw = b_12.zw;
;                 Q2[24] = Q2[24] * d_12.xy + (saq2 * bxy + vv2 * k_12.xy); Q2[25] = Q2[25] * d_12.zw + (saq2 * bzw + vv2 * k_12.zw);
;                 P2[24] = P2[24] * d_12.xy + sap2 * bxy; P2[25] = P2[25] * d_12.zw + sap2 * bzw;
;                 DPPFMAC(yd0, xrq3, Q2[24].x, 0); DPPFMAC(zd0, xrq3, P2[24].x, 0);
;                 DPPFMAC(yd1, xrq3, Q2[24].y, 1); DPPFMAC(zd1, xrq3, P2[24].y, 1);
;                 DPPFMAC(yd2, xrq3, Q2[25].x, 2); DPPFMAC(zd2, xrq3, P2[25].x, 2);
;                 DPPFMAC(yd3, xrq3, Q2[25].y, 3); DPPFMAC(zd3, xrq3, P2[25].y, 3);
;                 }
;                 { const f32x2 bxy = b_13.xy, bzw = b_13.zw;
;                 Q2[26] = Q2[26] * d_13.xy + (saq2 * bxy + vv2 * k_13.xy); Q2[27] = Q2[27] * d_13.zw + (saq2 * bzw + vv2 * k_13.zw);
	v_fmac_f32_e32 v211, v47, v203
	v_fmac_f32_e32 v215, v111, v203
	v_mfma_f32_4x4x1_16b_f32 v[52:55], v254, v175, v[52:55]
	v_mfma_f32_4x4x1_16b_f32 v[60:63], v178, v239, v[60:63]
	v_fmac_f32_e32 v208, v48, v204
	v_fmac_f32_e32 v212, v112, v204
	v_fmac_f32_e32 v209, v49, v204
	v_fmac_f32_e32 v213, v113, v204
	v_mfma_f32_4x4x1_16b_f32 v[124:127], v179, v239, v[124:127]
	v_fmac_f32_e32 v210, v50, v204
	v_fmac_f32_e32 v214, v114, v204
	v_fmac_f32_e32 v211, v51, v204
	v_fmac_f32_e32 v215, v115, v204
	v_mfma_f32_4x4x1_16b_f32 v[56:59], v254, v176, v[56:59]
	v_fmac_f32_e32 v208, v52, v205
	v_fmac_f32_e32 v212, v116, v205
	v_fmac_f32_e32 v209, v53, v205
	v_fmac_f32_e32 v213, v117, v205
	v_fmac_f32_e32 v210, v54, v205
	v_fmac_f32_e32 v214, v118, v205
	v_fmac_f32_e32 v211, v55, v205
	v_fmac_f32_e32 v215, v119, v205
	v_mfma_f32_4x4x1_16b_f32 v[60:63], v254, v177, v[60:63]
	v_fmac_f32_e32 v208, v56, v206
	v_fmac_f32_e32 v212, v120, v206
	v_fmac_f32_e32 v209, v57, v206
	v_fmac_f32_e32 v213, v121, v206
	v_fmac_f32_e32 v210, v58, v206
	v_fmac_f32_e32 v214, v122, v206
	v_fmac_f32_e32 v211, v59, v206
	v_fmac_f32_e32 v215, v123, v206
	v_fmac_f32_e32 v208, v60, v207
	v_fmac_f32_e32 v212, v124, v207
	v_fmac_f32_e32 v209, v61, v207
	v_fmac_f32_e32 v213, v125, v207
	v_fmac_f32_e32 v210, v62, v207
	v_fmac_f32_e32 v214, v126, v207
	v_fmac_f32_e32 v211, v63, v207
	v_fmac_f32_e32 v215, v127, v207
	v_add_f32_dpp v208, v208, v208 quad_perm:[1,0,3,2] row_mask:0xf bank_mask:0xf
	v_add_f32_dpp v209, v209, v209 quad_perm:[1,0,3,2] row_mask:0xf bank_mask:0xf
	v_add_f32_dpp v210, v210, v210 quad_perm:[1,0,3,2] row_mask:0xf bank_mask:0xf
	v_add_f32_dpp v211, v211, v211 quad_perm:[1,0,3,2] row_mask:0xf bank_mask:0xf
	v_add_f32_dpp v212, v212, v212 quad_perm:[1,0,3,2] row_mask:0xf bank_mask:0xf
	v_add_f32_dpp v213, v213, v213 quad_perm:[1,0,3,2] row_mask:0xf bank_mask:0xf
	v_add_f32_dpp v214, v214, v214 quad_perm:[1,0,3,2] row_mask:0xf bank_mask:0xf
	v_add_f32_dpp v215, v215, v215 quad_perm:[1,0,3,2] row_mask:0xf bank_mask:0xf
	v_add_f32_dpp v208, v208, v208 quad_perm:[2,3,0,1] row_mask:0xf bank_mask:0xf
	v_add_f32_dpp v209, v209, v209 quad_perm:[2,3,0,1] row_mask:0xf bank_mask:0xf
	v_add_f32_dpp v210, v210, v210 quad_perm:[2,3,0,1] row_mask:0xf bank_mask:0xf
	v_add_f32_dpp v211, v211, v211 quad_perm:[2,3,0,1] row_mask:0xf bank_mask:0xf
	v_add_f32_dpp v212, v212, v212 quad_perm:[2,3,0,1] row_mask:0xf bank_mask:0xf
	v_add_f32_dpp v213, v213, v213 quad_perm:[2,3,0,1] row_mask:0xf bank_mask:0xf
	v_add_f32_dpp v214, v214, v214 quad_perm:[2,3,0,1] row_mask:0xf bank_mask:0xf
	v_add_f32_dpp v215, v215, v215 quad_perm:[2,3,0,1] row_mask:0xf bank_mask:0xf
	v_cndmask_b32_e64 v178, v208, v209, s[86:87]
	v_cndmask_b32_e64 v179, v212, v213, s[86:87]
	v_cndmask_b32_e64 v178, v178, v210, s[88:89]
	v_cndmask_b32_e64 v179, v179, v214, s[88:89]
	v_cndmask_b32_e64 v178, v178, v211, s[84:85]
	v_cndmask_b32_e64 v179, v179, v215, s[84:85]
	v_add_u32_e32 v130, s45, v141
	v_lshl_add_u64 v[166:167], v[130:131], 2, s[26:27]
	v_lshl_add_u64 v[168:169], v[130:131], 1, s[12:13]
	v_bfe_u32 v130, v179, 16, 1
	v_add3_u32 v130, v179, v130, s41
	s_addk_i32 s45, 0x400
	v_add_u32_e32 v158, 0x600, v158
	global_store_dword v[166:167], v178, off
	global_store_short_d16_hi v[168:169], v130, off
	s_cmpk_eq_i32 s45, 0x1000
	s_cbranch_scc0 .Lp5_step
	s_andn2_b64 vcc, exec, s[66:67]
	s_cbranch_vccnz .LBB0_1077
	v_sub_f32_e32 v157, v157, v142
	v_sub_f32_e32 v130, v159, v143
	v_fma_f32 v157, v183, v157, v142
	v_add_f32_e32 v159, -1.0, v146
	v_mul_f32_e32 v158, v185, v157
	v_fma_f32 v159, v186, v159, 1.0
	v_fma_f32 v130, v182, v130, v143
	v_mul_f32_e32 v157, v159, v157
	v_mul_f32_e32 v159, v158, v158
	v_mul_f32_e32 v165, v130, v157
	v_mul_f32_e32 v166, v187, v165
	v_mov_b32_dpp v159, v159 row_shr:1 row_mask:0xf bank_mask:0xf bound_ctrl:1
	v_fmac_f32_e32 v159, v158, v158
	v_mov_b32_dpp v166, v166 row_shr:1 row_mask:0xf bank_mask:0xf bound_ctrl:1
	v_fmac_f32_e32 v166, v187, v165
	v_add_f32_dpp v159, v159, v159 row_shr:2 row_mask:0xf bank_mask:0xf bound_ctrl:1
	s_lshl_b32 s43, s43, 2
	v_add_f32_dpp v165, v166, v166 row_shr:2 row_mask:0xf bank_mask:0xf bound_ctrl:1
	v_add_f32_dpp v159, v159, v159 row_shr:4 row_mask:0xf bank_mask:0xf bound_ctrl:1
	v_mov_b32_e32 v166, v131
	v_add_f32_dpp v165, v165, v165 row_shr:4 row_mask:0xf bank_mask:0xf bound_ctrl:1
	v_add_f32_dpp v159, v159, v159 row_shr:8 row_mask:0xf bank_mask:0xf bound_ctrl:1
	s_and_b32 s43, s43, 4
	v_add_f32_dpp v165, v165, v165 row_shr:8 row_mask:0xf bank_mask:0xf bound_ctrl:1
	v_mov_b32_dpp v166, v159 row_bcast:15 row_mask:0xa bank_mask:0xf
	v_add_f32_e32 v159, v159, v166
	v_mov_b32_e32 v166, v131
	s_xor_b32 s46, s43, 4
	s_mulk_i32 s46, 0x600
	v_mov_b32_dpp v166, v165 row_bcast:15 row_mask:0xa bank_mask:0xf
	v_add_f32_e32 v165, v165, v166
	v_mov_b32_e32 v166, v131
	v_sub_f32_e32 v156, v156, v133
	v_fma_f32 v156, v184, v156, v133
	v_mov_b32_dpp v166, v159 row_bcast:31 row_mask:0xc bank_mask:0xf
	v_add_f32_e32 v159, v159, v166
	v_mov_b32_e32 v166, v131
	v_readlane_b32 s45, v159, 63
	s_nop 0
	v_mov_b32_dpp v166, v165 row_bcast:31 row_mask:0xc bank_mask:0xf
	v_max_f32_e64 v159, s45, s45
	v_max_f32_e32 v159, 0x179abe15, v159
	v_rsq_f32_e32 v159, v159
	v_add_f32_e32 v165, v165, v166
	v_mul_f32_e32 v158, v158, v159
	v_add_u32_e32 v159, s46, v180
	ds_write2st64_b32 v159, v189, v158 offset1:1
	v_mul_f32_e32 v158, v146, v158
	v_readlane_b32 s45, v165, 63
	ds_write2st64_b32 v159, v158, v157 offset0:2 offset1:3
	ds_write2st64_b32 v159, v156, v130 offset0:4 offset1:5
	v_bfe_u32 v130, v156, 16, 1
	v_mov_b32_e32 v165, v131
	v_add3_u32 v130, v156, v130, s41
	v_lshl_add_u64 v[156:157], v[164:165], 1, s[18:19]
	global_store_short_d16_hi v[156:157], v130, off
	s_and_saveexec_b64 s[66:67], s[4:5]
	s_cbranch_execz .LBB0_1070
	v_lshl_add_u32 v130, s44, 6, v140
	v_lshl_add_u64 v[156:157], v[130:131], 2, s[36:37]
	v_mov_b32_e32 v130, s45
	global_store_dword v[156:157], v130, off
